# v36
# baseline (speedup 1.0000x reference)
.LBB0_711:
	v_lshl_add_u32 v144, s28, 8, v133
	s_lshl_b32 s12, s8, 8
	s_ashr_i32 s13, s12, 31
	v_ashrrev_i32_e32 v145, 31, v144
	v_mov_b32_e32 v143, s13
	v_or_b32_e32 v142, s12, v132
	v_lshlrev_b64 v[152:153], 10, v[144:145]
	v_lshl_add_u64 v[156:157], v[152:153], 0, v[142:143]
	v_lshl_add_u64 v[158:159], v[156:157], 2, s[52:53]
	global_load_dwordx4 v[164:167], v[158:159], off
	global_load_dwordx4 v[168:171], v[158:159], off offset:64
	global_load_dwordx4 v[172:175], v[158:159], off offset:512
	global_load_dwordx4 v[176:179], v[158:159], off offset:576
	v_add_co_u32_e32 v184, vcc, 0x10000, v158
	s_nop 1
	v_addc_co_u32_e32 v185, vcc, 0, v159, vcc
	global_load_dwordx4 v[180:183], v[184:185], off
	global_load_dwordx4 v[188:191], v[184:185], off offset:64
	global_load_dwordx4 v[192:195], v[184:185], off offset:512
	global_load_dwordx4 v[196:199], v[184:185], off offset:576
	v_add_co_u32_e32 v184, vcc, 0x20000, v158
	s_nop 1
	v_addc_co_u32_e32 v185, vcc, 0, v159, vcc
	global_load_dwordx4 v[200:203], v[184:185], off
	global_load_dwordx4 v[204:207], v[184:185], off offset:64
	global_load_dwordx4 v[208:211], v[184:185], off offset:512
	global_load_dwordx4 v[212:215], v[184:185], off offset:576
	v_add_co_u32_e32 v184, vcc, 0x30000, v158
	s_nop 1
	v_addc_co_u32_e32 v185, vcc, 0, v159, vcc
	global_load_dwordx4 v[216:219], v[184:185], off
	global_load_dwordx4 v[220:223], v[184:185], off offset:64
	global_load_dwordx4 v[224:227], v[184:185], off offset:512
	global_load_dwordx4 v[228:231], v[184:185], off offset:576
	s_waitcnt vmcnt(0)
	v_lshlrev_b64 v[156:157], 1, v[156:157]
	v_lshl_add_u64 v[160:161], s[62:63], 0, v[156:157]
	v_xor_b32_e32 v151, 32, v150
	s_lshl_b32 s28, s8, 2
	s_ashr_i32 s29, s28, 31
	v_mov_b64_e32 v[152:153], v[164:165]
	v_mov_b64_e32 v[154:155], v[166:167]
	v_pk_add_f32 v[154:155], v[126:127], v[154:155]
	v_pk_add_f32 v[152:153], v[124:125], v[152:153]
	s_nop 0
	v_cvt_pk_bf16_f32 v124, v152, v153
	v_cvt_pk_bf16_f32 v125, v154, v155
	global_store_dwordx2 v[160:161], v[124:125], off
	v_or_b32_e32 v160, 32, v156
	v_mov_b32_e32 v161, v157
	v_lshl_add_u64 v[160:161], s[62:63], 0, v[160:161]
	v_mul_f32_e32 v153, v153, v153
	v_mul_f32_e32 v155, v155, v155
	v_fmac_f32_e32 v153, v152, v152
	v_fmac_f32_e32 v155, v154, v154
	v_add_f32_e32 v152, v153, v155
	v_mov_b64_e32 v[124:125], v[168:169]
	v_mov_b64_e32 v[126:127], v[170:171]
	v_pk_add_f32 v[126:127], v[122:123], v[126:127]
	v_pk_add_f32 v[124:125], v[120:121], v[124:125]
	s_nop 0
	v_cvt_pk_bf16_f32 v120, v124, v125
	v_cvt_pk_bf16_f32 v121, v126, v127
	global_store_dwordx2 v[160:161], v[120:121], off
	v_or_b32_e32 v160, 0x100, v156
	v_mov_b32_e32 v161, v157
	v_lshl_add_u64 v[160:161], s[62:63], 0, v[160:161]
	v_mul_f32_e32 v125, v125, v125
	v_mul_f32_e32 v127, v127, v127
	v_fmac_f32_e32 v125, v124, v124
	v_fmac_f32_e32 v127, v126, v126
	v_add_f32_e32 v124, v125, v127
	v_add_f32_e32 v124, v152, v124
	v_or_b32_e32 v156, 0x120, v156
	v_mov_b64_e32 v[120:121], v[172:173]
	v_mov_b64_e32 v[122:123], v[174:175]
	v_pk_add_f32 v[122:123], v[118:119], v[122:123]
	v_pk_add_f32 v[162:163], v[116:117], v[120:121]
	s_nop 0
	v_cvt_pk_bf16_f32 v116, v162, v163
	v_cvt_pk_bf16_f32 v117, v122, v123
	global_store_dwordx2 v[160:161], v[116:117], off
	v_and_b32_e32 v117, 64, v150
	v_mul_f32_e32 v125, v163, v163
	v_mul_f32_e32 v123, v123, v123
	v_xor_b32_e32 v116, 16, v150
	v_add_u32_e32 v117, 64, v117
	v_fmac_f32_e32 v125, v162, v162
	v_fmac_f32_e32 v123, v122, v122
	v_cmp_lt_i32_e32 vcc, v116, v117
	v_add_f32_e32 v122, v125, v123
	v_add_f32_e32 v122, v124, v122
	v_cndmask_b32_e32 v116, v150, v116, vcc
	v_lshlrev_b32_e32 v116, 2, v116
	v_cmp_lt_i32_e32 vcc, v151, v117
	v_mov_b64_e32 v[118:119], v[176:177]
	v_mov_b64_e32 v[120:121], v[178:179]
	v_pk_add_f32 v[120:121], v[114:115], v[120:121]
	v_pk_add_f32 v[112:113], v[112:113], v[118:119]
	v_mul_f32_e32 v115, v121, v121
	v_mul_f32_e32 v114, v113, v113
	v_fmac_f32_e32 v114, v112, v112
	v_fmac_f32_e32 v115, v120, v120
	v_add_f32_e32 v114, v114, v115
	v_add_f32_e32 v114, v122, v114
	ds_bpermute_b32 v115, v116, v114
	v_cndmask_b32_e32 v117, v150, v151, vcc
	v_cvt_pk_bf16_f32 v118, v112, v113
	v_cvt_pk_bf16_f32 v119, v120, v121
	v_lshl_add_u64 v[120:121], s[62:63], 0, v[156:157]
	s_waitcnt lgkmcnt(0)
	v_add_f32_e32 v112, v114, v115
	v_lshlrev_b32_e32 v114, 2, v117
	ds_bpermute_b32 v113, v114, v112
	global_store_dwordx2 v[120:121], v[118:119], off
	s_and_saveexec_b64 s[30:31], s[4:5]
	s_cbranch_execz .LBB0_713
	v_lshlrev_b64 v[118:119], 6, v[144:145]
	v_lshl_add_u64 v[118:119], s[60:61], 0, v[118:119]
	v_lshl_add_u64 v[118:119], s[28:29], 2, v[118:119]
	s_lshl_b32 s8, s47, 2
	v_lshl_add_u64 v[118:119], v[118:119], 0, s[8:9]
	s_waitcnt lgkmcnt(0)
	v_add_f32_e32 v112, v112, v113
	global_store_dword v[118:119], v112, off
.LBB0_713:
	s_or_b64 exec, exec, s[30:31]
	v_or_b32_e32 v112, 16, v144
	s_waitcnt lgkmcnt(0)
	v_ashrrev_i32_e32 v113, 31, v112
	v_lshlrev_b64 v[118:119], 10, v[112:113]
	v_lshl_add_u64 v[122:123], v[118:119], 0, v[142:143]
	v_lshl_add_u64 v[124:125], v[122:123], 2, s[52:53]
	v_lshlrev_b64 v[122:123], 1, v[122:123]
	v_lshl_add_u64 v[126:127], s[62:63], 0, v[122:123]
	v_mov_b64_e32 v[118:119], v[180:181]
	v_mov_b64_e32 v[120:121], v[182:183]
	v_pk_add_f32 v[120:121], v[110:111], v[120:121]
	v_pk_add_f32 v[118:119], v[108:109], v[118:119]
	v_mul_f32_e32 v117, v121, v121
	v_cvt_pk_bf16_f32 v108, v118, v119
	v_cvt_pk_bf16_f32 v109, v120, v121
	global_store_dwordx2 v[126:127], v[108:109], off
	v_or_b32_e32 v126, 32, v122
	v_mov_b32_e32 v127, v123
	v_lshl_add_u64 v[126:127], s[62:63], 0, v[126:127]
	v_mul_f32_e32 v115, v119, v119
	v_fmac_f32_e32 v115, v118, v118
	v_fmac_f32_e32 v117, v120, v120
	v_add_f32_e32 v115, v115, v117
	v_mov_b64_e32 v[108:109], v[188:189]
	v_mov_b64_e32 v[110:111], v[190:191]
	v_pk_add_f32 v[110:111], v[106:107], v[110:111]
	v_pk_add_f32 v[108:109], v[104:105], v[108:109]
	s_nop 0
	v_cvt_pk_bf16_f32 v104, v108, v109
	v_cvt_pk_bf16_f32 v105, v110, v111
	global_store_dwordx2 v[126:127], v[104:105], off
	v_or_b32_e32 v126, 0x100, v122
	v_mov_b32_e32 v127, v123
	v_lshl_add_u64 v[126:127], s[62:63], 0, v[126:127]
	v_mul_f32_e32 v109, v109, v109
	v_mul_f32_e32 v111, v111, v111
	v_fmac_f32_e32 v109, v108, v108
	v_fmac_f32_e32 v111, v110, v110
	v_add_f32_e32 v108, v109, v111
	v_add_f32_e32 v108, v115, v108
	v_or_b32_e32 v122, 0x120, v122
	v_mov_b64_e32 v[104:105], v[192:193]
	v_mov_b64_e32 v[106:107], v[194:195]
	v_pk_add_f32 v[106:107], v[102:103], v[106:107]
	v_pk_add_f32 v[104:105], v[100:101], v[104:105]
	s_nop 0
	v_cvt_pk_bf16_f32 v100, v104, v105
	v_cvt_pk_bf16_f32 v101, v106, v107
	global_store_dwordx2 v[126:127], v[100:101], off
	v_mul_f32_e32 v105, v105, v105
	v_mul_f32_e32 v107, v107, v107
	v_fmac_f32_e32 v105, v104, v104
	v_fmac_f32_e32 v107, v106, v106
	v_add_f32_e32 v104, v105, v107
	v_add_f32_e32 v104, v108, v104
	v_mov_b64_e32 v[100:101], v[196:197]
	v_mov_b64_e32 v[102:103], v[198:199]
	v_pk_add_f32 v[98:99], v[98:99], v[102:103]
	v_pk_add_f32 v[96:97], v[96:97], v[100:101]
	v_mul_f32_e32 v101, v99, v99
	v_mul_f32_e32 v100, v97, v97
	v_fmac_f32_e32 v100, v96, v96
	v_fmac_f32_e32 v101, v98, v98
	v_add_f32_e32 v100, v100, v101
	v_add_f32_e32 v101, v104, v100
	ds_bpermute_b32 v102, v116, v101
	v_cvt_pk_bf16_f32 v100, v96, v97
	s_waitcnt lgkmcnt(0)
	v_add_f32_e32 v96, v101, v102
	ds_bpermute_b32 v97, v114, v96
	v_cvt_pk_bf16_f32 v101, v98, v99
	v_lshl_add_u64 v[98:99], s[62:63], 0, v[122:123]
	global_store_dwordx2 v[98:99], v[100:101], off
	s_and_saveexec_b64 s[30:31], s[4:5]
	s_cbranch_execz .LBB0_715
	v_lshlrev_b64 v[98:99], 6, v[112:113]
	v_lshl_add_u64 v[98:99], s[60:61], 0, v[98:99]
	v_lshl_add_u64 v[98:99], s[28:29], 2, v[98:99]
	s_lshl_b32 s8, s47, 2
	v_lshl_add_u64 v[98:99], v[98:99], 0, s[8:9]
	s_waitcnt lgkmcnt(0)
	v_add_f32_e32 v96, v96, v97
	global_store_dword v[98:99], v96, off
.LBB0_715:
	s_or_b64 exec, exec, s[30:31]
	v_or_b32_e32 v96, 32, v144
	s_waitcnt lgkmcnt(0)
	v_ashrrev_i32_e32 v97, 31, v96
	v_lshlrev_b64 v[98:99], 10, v[96:97]
	v_lshl_add_u64 v[102:103], v[98:99], 0, v[142:143]
	v_lshl_add_u64 v[104:105], v[102:103], 2, s[52:53]
	v_lshlrev_b64 v[102:103], 1, v[102:103]
	v_lshl_add_u64 v[106:107], s[62:63], 0, v[102:103]
	v_mov_b64_e32 v[98:99], v[200:201]
	v_mov_b64_e32 v[100:101], v[202:203]
	v_pk_add_f32 v[100:101], v[94:95], v[100:101]
	v_pk_add_f32 v[98:99], v[92:93], v[98:99]
	s_nop 0
	v_cvt_pk_bf16_f32 v92, v98, v99
	v_cvt_pk_bf16_f32 v93, v100, v101
	global_store_dwordx2 v[106:107], v[92:93], off
	v_or_b32_e32 v106, 32, v102
	v_mov_b32_e32 v107, v103
	v_lshl_add_u64 v[106:107], s[62:63], 0, v[106:107]
	v_mul_f32_e32 v99, v99, v99
	v_mul_f32_e32 v101, v101, v101
	v_fmac_f32_e32 v99, v98, v98
	v_fmac_f32_e32 v101, v100, v100
	v_add_f32_e32 v98, v99, v101
	v_mov_b64_e32 v[92:93], v[204:205]
	v_mov_b64_e32 v[94:95], v[206:207]
	v_pk_add_f32 v[94:95], v[90:91], v[94:95]
	v_pk_add_f32 v[92:93], v[88:89], v[92:93]
	s_nop 0
	v_cvt_pk_bf16_f32 v88, v92, v93
	v_cvt_pk_bf16_f32 v89, v94, v95
	global_store_dwordx2 v[106:107], v[88:89], off
	v_or_b32_e32 v106, 0x100, v102
	v_mov_b32_e32 v107, v103
	v_lshl_add_u64 v[106:107], s[62:63], 0, v[106:107]
	v_mul_f32_e32 v93, v93, v93
	v_mul_f32_e32 v95, v95, v95
	v_fmac_f32_e32 v93, v92, v92
	v_fmac_f32_e32 v95, v94, v94
	v_add_f32_e32 v92, v93, v95
	v_add_f32_e32 v92, v98, v92
	v_or_b32_e32 v102, 0x120, v102
	v_mov_b64_e32 v[88:89], v[208:209]
	v_mov_b64_e32 v[90:91], v[210:211]
	v_pk_add_f32 v[90:91], v[86:87], v[90:91]
	v_pk_add_f32 v[88:89], v[84:85], v[88:89]
	s_nop 0
	v_cvt_pk_bf16_f32 v84, v88, v89
	v_cvt_pk_bf16_f32 v85, v90, v91
	global_store_dwordx2 v[106:107], v[84:85], off
	v_mul_f32_e32 v89, v89, v89
	v_mul_f32_e32 v91, v91, v91
	v_fmac_f32_e32 v89, v88, v88
	v_fmac_f32_e32 v91, v90, v90
	v_add_f32_e32 v88, v89, v91
	v_add_f32_e32 v88, v92, v88
	v_mov_b64_e32 v[84:85], v[212:213]
	v_mov_b64_e32 v[86:87], v[214:215]
	v_pk_add_f32 v[82:83], v[82:83], v[86:87]
	v_pk_add_f32 v[80:81], v[80:81], v[84:85]
	v_mul_f32_e32 v85, v83, v83
	v_mul_f32_e32 v84, v81, v81
	v_fmac_f32_e32 v84, v80, v80
	v_fmac_f32_e32 v85, v82, v82
	v_add_f32_e32 v84, v84, v85
	v_add_f32_e32 v85, v88, v84
	ds_bpermute_b32 v86, v116, v85
	v_cvt_pk_bf16_f32 v84, v80, v81
	s_waitcnt lgkmcnt(0)
	v_add_f32_e32 v80, v85, v86
	ds_bpermute_b32 v81, v114, v80
	v_cvt_pk_bf16_f32 v85, v82, v83
	v_lshl_add_u64 v[82:83], s[62:63], 0, v[102:103]
	global_store_dwordx2 v[82:83], v[84:85], off
	s_and_saveexec_b64 s[30:31], s[4:5]
	s_cbranch_execz .LBB0_717
	v_lshlrev_b64 v[82:83], 6, v[96:97]
	v_lshl_add_u64 v[82:83], s[60:61], 0, v[82:83]
	v_lshl_add_u64 v[82:83], s[28:29], 2, v[82:83]
	s_lshl_b32 s8, s47, 2
	v_lshl_add_u64 v[82:83], v[82:83], 0, s[8:9]
	s_waitcnt lgkmcnt(0)
	v_add_f32_e32 v80, v80, v81
	global_store_dword v[82:83], v80, off
.LBB0_717:
	s_or_b64 exec, exec, s[30:31]
	v_or_b32_e32 v80, 48, v144
	s_waitcnt lgkmcnt(0)
	v_ashrrev_i32_e32 v81, 31, v80
	v_lshlrev_b64 v[82:83], 10, v[80:81]
	v_lshl_add_u64 v[86:87], v[82:83], 0, v[142:143]
	v_lshl_add_u64 v[88:89], v[86:87], 2, s[52:53]
	v_lshlrev_b64 v[86:87], 1, v[86:87]
	v_lshl_add_u64 v[90:91], s[62:63], 0, v[86:87]
	v_mov_b64_e32 v[82:83], v[216:217]
	v_mov_b64_e32 v[84:85], v[218:219]
	v_pk_add_f32 v[84:85], v[78:79], v[84:85]
	v_pk_add_f32 v[82:83], v[76:77], v[82:83]
	s_nop 0
	v_cvt_pk_bf16_f32 v76, v82, v83
	v_cvt_pk_bf16_f32 v77, v84, v85
	global_store_dwordx2 v[90:91], v[76:77], off
	v_or_b32_e32 v90, 32, v86
	v_mov_b32_e32 v91, v87
	v_lshl_add_u64 v[90:91], s[62:63], 0, v[90:91]
	v_mul_f32_e32 v83, v83, v83
	v_mul_f32_e32 v85, v85, v85
	v_fmac_f32_e32 v83, v82, v82
	v_fmac_f32_e32 v85, v84, v84
	v_add_f32_e32 v82, v83, v85
	v_mov_b64_e32 v[76:77], v[220:221]
	v_mov_b64_e32 v[78:79], v[222:223]
	v_pk_add_f32 v[78:79], v[74:75], v[78:79]
	v_pk_add_f32 v[76:77], v[72:73], v[76:77]
	s_nop 0
	v_cvt_pk_bf16_f32 v72, v76, v77
	v_cvt_pk_bf16_f32 v73, v78, v79
	global_store_dwordx2 v[90:91], v[72:73], off
	v_or_b32_e32 v90, 0x100, v86
	v_mov_b32_e32 v91, v87
	v_lshl_add_u64 v[90:91], s[62:63], 0, v[90:91]
	v_mul_f32_e32 v77, v77, v77
	v_mul_f32_e32 v79, v79, v79
	v_fmac_f32_e32 v77, v76, v76
	v_fmac_f32_e32 v79, v78, v78
	v_add_f32_e32 v76, v77, v79
	v_add_f32_e32 v76, v82, v76
	v_or_b32_e32 v86, 0x120, v86
	v_mov_b64_e32 v[72:73], v[224:225]
	v_mov_b64_e32 v[74:75], v[226:227]
	v_pk_add_f32 v[74:75], v[70:71], v[74:75]
	v_pk_add_f32 v[72:73], v[68:69], v[72:73]
	s_nop 0
	v_cvt_pk_bf16_f32 v68, v72, v73
	v_cvt_pk_bf16_f32 v69, v74, v75
	global_store_dwordx2 v[90:91], v[68:69], off
	v_mul_f32_e32 v73, v73, v73
	v_mul_f32_e32 v75, v75, v75
	v_fmac_f32_e32 v73, v72, v72
	v_fmac_f32_e32 v75, v74, v74
	v_add_f32_e32 v72, v73, v75
	v_add_f32_e32 v72, v76, v72
	v_mov_b64_e32 v[68:69], v[228:229]
	v_mov_b64_e32 v[70:71], v[230:231]
	v_pk_add_f32 v[66:67], v[66:67], v[70:71]
	v_pk_add_f32 v[64:65], v[64:65], v[68:69]
	v_mul_f32_e32 v69, v67, v67
	v_mul_f32_e32 v68, v65, v65
	v_fmac_f32_e32 v68, v64, v64
	v_fmac_f32_e32 v69, v66, v66
	v_add_f32_e32 v68, v68, v69
	v_add_f32_e32 v69, v72, v68
	ds_bpermute_b32 v70, v116, v69
	v_cvt_pk_bf16_f32 v68, v64, v65
	s_waitcnt lgkmcnt(0)
	v_add_f32_e32 v64, v69, v70
	ds_bpermute_b32 v65, v114, v64
	v_cvt_pk_bf16_f32 v69, v66, v67
	v_lshl_add_u64 v[66:67], s[62:63], 0, v[86:87]
	global_store_dwordx2 v[66:67], v[68:69], off
	s_and_saveexec_b64 s[30:31], s[4:5]
	s_cbranch_execz .LBB0_719
	v_lshlrev_b64 v[66:67], 6, v[80:81]
	v_lshl_add_u64 v[66:67], s[60:61], 0, v[66:67]
	v_lshl_add_u64 v[66:67], s[28:29], 2, v[66:67]
	s_lshl_b32 s8, s47, 2
	v_lshl_add_u64 v[66:67], v[66:67], 0, s[8:9]
	s_waitcnt lgkmcnt(0)
	v_add_f32_e32 v64, v64, v65
	global_store_dword v[66:67], v64, off
.LBB0_719:
	s_or_b64 exec, exec, s[30:31]
	v_add_u32_e32 v64, 0x80, v144
	s_waitcnt lgkmcnt(0)
	v_ashrrev_i32_e32 v65, 31, v64
	v_lshlrev_b64 v[66:67], 10, v[64:65]
	v_lshl_add_u64 v[70:71], v[66:67], 0, v[142:143]
	v_lshl_add_u64 v[72:73], v[70:71], 2, s[52:53]
	global_load_dwordx4 v[164:167], v[72:73], off
	global_load_dwordx4 v[168:171], v[72:73], off offset:64
	global_load_dwordx4 v[172:175], v[72:73], off offset:512
	global_load_dwordx4 v[176:179], v[72:73], off offset:576
	v_add_co_u32_e32 v184, vcc, 0x10000, v72
	s_nop 1
	v_addc_co_u32_e32 v185, vcc, 0, v73, vcc
	global_load_dwordx4 v[180:183], v[184:185], off
	global_load_dwordx4 v[188:191], v[184:185], off offset:64
	global_load_dwordx4 v[192:195], v[184:185], off offset:512
	global_load_dwordx4 v[196:199], v[184:185], off offset:576
	v_add_co_u32_e32 v184, vcc, 0x20000, v72
	s_nop 1
	v_addc_co_u32_e32 v185, vcc, 0, v73, vcc
	global_load_dwordx4 v[200:203], v[184:185], off
	global_load_dwordx4 v[204:207], v[184:185], off offset:64
	global_load_dwordx4 v[208:211], v[184:185], off offset:512
	global_load_dwordx4 v[212:215], v[184:185], off offset:576
	v_add_co_u32_e32 v184, vcc, 0x30000, v72
	s_nop 1
	v_addc_co_u32_e32 v185, vcc, 0, v73, vcc
	global_load_dwordx4 v[216:219], v[184:185], off
	global_load_dwordx4 v[220:223], v[184:185], off offset:64
	global_load_dwordx4 v[224:227], v[184:185], off offset:512
	global_load_dwordx4 v[228:231], v[184:185], off offset:576
	s_waitcnt vmcnt(0)
	v_lshlrev_b64 v[70:71], 1, v[70:71]
	v_lshl_add_u64 v[74:75], s[62:63], 0, v[70:71]
	v_mov_b64_e32 v[66:67], v[164:165]
	v_mov_b64_e32 v[68:69], v[166:167]
	v_pk_add_f32 v[68:69], v[62:63], v[68:69]
	v_pk_add_f32 v[66:67], v[60:61], v[66:67]
	s_nop 0
	v_cvt_pk_bf16_f32 v60, v66, v67
	v_cvt_pk_bf16_f32 v61, v68, v69
	global_store_dwordx2 v[74:75], v[60:61], off
	v_or_b32_e32 v74, 32, v70
	v_mov_b32_e32 v75, v71
	v_lshl_add_u64 v[74:75], s[62:63], 0, v[74:75]
	v_mul_f32_e32 v67, v67, v67
	v_mul_f32_e32 v69, v69, v69
	v_fmac_f32_e32 v67, v66, v66
	v_fmac_f32_e32 v69, v68, v68
	v_add_f32_e32 v66, v67, v69
	v_mov_b64_e32 v[60:61], v[168:169]
	v_mov_b64_e32 v[62:63], v[170:171]
	v_pk_add_f32 v[62:63], v[58:59], v[62:63]
	v_pk_add_f32 v[60:61], v[56:57], v[60:61]
	s_nop 0
	v_cvt_pk_bf16_f32 v56, v60, v61
	v_cvt_pk_bf16_f32 v57, v62, v63
	global_store_dwordx2 v[74:75], v[56:57], off
	v_or_b32_e32 v74, 0x100, v70
	v_mov_b32_e32 v75, v71
	v_lshl_add_u64 v[74:75], s[62:63], 0, v[74:75]
	v_mul_f32_e32 v61, v61, v61
	v_mul_f32_e32 v63, v63, v63
	v_fmac_f32_e32 v61, v60, v60
	v_fmac_f32_e32 v63, v62, v62
	v_add_f32_e32 v60, v61, v63
	v_add_f32_e32 v60, v66, v60
	v_or_b32_e32 v70, 0x120, v70
	v_mov_b64_e32 v[56:57], v[172:173]
	v_mov_b64_e32 v[58:59], v[174:175]
	v_pk_add_f32 v[58:59], v[54:55], v[58:59]
	v_pk_add_f32 v[56:57], v[52:53], v[56:57]
	s_nop 0
	v_cvt_pk_bf16_f32 v52, v56, v57
	v_cvt_pk_bf16_f32 v53, v58, v59
	global_store_dwordx2 v[74:75], v[52:53], off
	v_mul_f32_e32 v57, v57, v57
	v_mul_f32_e32 v59, v59, v59
	v_fmac_f32_e32 v57, v56, v56
	v_fmac_f32_e32 v59, v58, v58
	v_add_f32_e32 v56, v57, v59
	v_add_f32_e32 v56, v60, v56
	v_mov_b64_e32 v[52:53], v[176:177]
	v_mov_b64_e32 v[54:55], v[178:179]
	v_pk_add_f32 v[50:51], v[50:51], v[54:55]
	v_pk_add_f32 v[48:49], v[48:49], v[52:53]
	v_mul_f32_e32 v53, v51, v51
	v_mul_f32_e32 v52, v49, v49
	v_fmac_f32_e32 v52, v48, v48
	v_fmac_f32_e32 v53, v50, v50
	v_add_f32_e32 v52, v52, v53
	v_add_f32_e32 v53, v56, v52
	ds_bpermute_b32 v54, v116, v53
	v_cvt_pk_bf16_f32 v52, v48, v49
	s_waitcnt lgkmcnt(0)
	v_add_f32_e32 v48, v53, v54
	ds_bpermute_b32 v49, v114, v48
	v_cvt_pk_bf16_f32 v53, v50, v51
	v_lshl_add_u64 v[50:51], s[62:63], 0, v[70:71]
	global_store_dwordx2 v[50:51], v[52:53], off
	s_and_saveexec_b64 s[30:31], s[4:5]
	s_cbranch_execz .LBB0_721
	v_lshlrev_b64 v[50:51], 6, v[64:65]
	v_lshl_add_u64 v[50:51], s[60:61], 0, v[50:51]
	v_lshl_add_u64 v[50:51], s[28:29], 2, v[50:51]
	s_lshl_b32 s8, s47, 2
	v_lshl_add_u64 v[50:51], v[50:51], 0, s[8:9]
	s_waitcnt lgkmcnt(0)
	v_add_f32_e32 v48, v48, v49
	global_store_dword v[50:51], v48, off
.LBB0_721:
	s_or_b64 exec, exec, s[30:31]
	v_add_u32_e32 v48, 0x90, v144
	s_waitcnt lgkmcnt(0)
	v_ashrrev_i32_e32 v49, 31, v48
	v_lshlrev_b64 v[50:51], 10, v[48:49]
	v_lshl_add_u64 v[54:55], v[50:51], 0, v[142:143]
	v_lshl_add_u64 v[56:57], v[54:55], 2, s[52:53]
	v_lshlrev_b64 v[54:55], 1, v[54:55]
	v_lshl_add_u64 v[58:59], s[62:63], 0, v[54:55]
	v_mov_b64_e32 v[50:51], v[180:181]
	v_mov_b64_e32 v[52:53], v[182:183]
	v_pk_add_f32 v[52:53], v[46:47], v[52:53]
	v_pk_add_f32 v[50:51], v[44:45], v[50:51]
	s_nop 0
	v_cvt_pk_bf16_f32 v44, v50, v51
	v_cvt_pk_bf16_f32 v45, v52, v53
	global_store_dwordx2 v[58:59], v[44:45], off
	v_or_b32_e32 v58, 32, v54
	v_mov_b32_e32 v59, v55
	v_lshl_add_u64 v[58:59], s[62:63], 0, v[58:59]
	v_mul_f32_e32 v51, v51, v51
	v_mul_f32_e32 v53, v53, v53
	v_fmac_f32_e32 v51, v50, v50
	v_fmac_f32_e32 v53, v52, v52
	v_add_f32_e32 v50, v51, v53
	v_mov_b64_e32 v[44:45], v[188:189]
	v_mov_b64_e32 v[46:47], v[190:191]
	v_pk_add_f32 v[46:47], v[42:43], v[46:47]
	v_pk_add_f32 v[44:45], v[40:41], v[44:45]
	s_nop 0
	v_cvt_pk_bf16_f32 v40, v44, v45
	v_cvt_pk_bf16_f32 v41, v46, v47
	global_store_dwordx2 v[58:59], v[40:41], off
	v_or_b32_e32 v58, 0x100, v54
	v_mov_b32_e32 v59, v55
	v_lshl_add_u64 v[58:59], s[62:63], 0, v[58:59]
	v_mul_f32_e32 v45, v45, v45
	v_mul_f32_e32 v47, v47, v47
	v_fmac_f32_e32 v45, v44, v44
	v_fmac_f32_e32 v47, v46, v46
	v_add_f32_e32 v44, v45, v47
	v_add_f32_e32 v44, v50, v44
	v_or_b32_e32 v54, 0x120, v54
	v_mov_b64_e32 v[40:41], v[192:193]
	v_mov_b64_e32 v[42:43], v[194:195]
	v_pk_add_f32 v[42:43], v[38:39], v[42:43]
	v_pk_add_f32 v[40:41], v[36:37], v[40:41]
	s_nop 0
	v_cvt_pk_bf16_f32 v36, v40, v41
	v_cvt_pk_bf16_f32 v37, v42, v43
	global_store_dwordx2 v[58:59], v[36:37], off
	v_mul_f32_e32 v41, v41, v41
	v_mul_f32_e32 v43, v43, v43
	v_fmac_f32_e32 v41, v40, v40
	v_fmac_f32_e32 v43, v42, v42
	v_add_f32_e32 v40, v41, v43
	v_add_f32_e32 v40, v44, v40
	v_mov_b64_e32 v[36:37], v[196:197]
	v_mov_b64_e32 v[38:39], v[198:199]
	v_pk_add_f32 v[34:35], v[34:35], v[38:39]
	v_pk_add_f32 v[32:33], v[32:33], v[36:37]
	v_mul_f32_e32 v37, v35, v35
	v_mul_f32_e32 v36, v33, v33
	v_fmac_f32_e32 v36, v32, v32
	v_fmac_f32_e32 v37, v34, v34
	v_add_f32_e32 v36, v36, v37
	v_add_f32_e32 v37, v40, v36
	ds_bpermute_b32 v38, v116, v37
	v_cvt_pk_bf16_f32 v36, v32, v33
	s_waitcnt lgkmcnt(0)
	v_add_f32_e32 v32, v37, v38
	ds_bpermute_b32 v33, v114, v32
	v_cvt_pk_bf16_f32 v37, v34, v35
	v_lshl_add_u64 v[34:35], s[62:63], 0, v[54:55]
	global_store_dwordx2 v[34:35], v[36:37], off
	s_and_saveexec_b64 s[30:31], s[4:5]
	s_cbranch_execz .LBB0_723
	v_lshlrev_b64 v[34:35], 6, v[48:49]
	v_lshl_add_u64 v[34:35], s[60:61], 0, v[34:35]
	v_lshl_add_u64 v[34:35], s[28:29], 2, v[34:35]
	s_lshl_b32 s8, s47, 2
	v_lshl_add_u64 v[34:35], v[34:35], 0, s[8:9]
	s_waitcnt lgkmcnt(0)
	v_add_f32_e32 v32, v32, v33
	global_store_dword v[34:35], v32, off
.LBB0_723:
	s_or_b64 exec, exec, s[30:31]
	v_add_u32_e32 v32, 0xa0, v144
	s_waitcnt lgkmcnt(0)
	v_ashrrev_i32_e32 v33, 31, v32
	v_lshlrev_b64 v[34:35], 10, v[32:33]
	v_lshl_add_u64 v[38:39], v[34:35], 0, v[142:143]
	v_lshl_add_u64 v[40:41], v[38:39], 2, s[52:53]
	v_lshlrev_b64 v[38:39], 1, v[38:39]
	v_lshl_add_u64 v[42:43], s[62:63], 0, v[38:39]
	v_mov_b64_e32 v[34:35], v[200:201]
	v_mov_b64_e32 v[36:37], v[202:203]
	v_pk_add_f32 v[36:37], v[30:31], v[36:37]
	v_pk_add_f32 v[34:35], v[28:29], v[34:35]
	s_nop 0
	v_cvt_pk_bf16_f32 v28, v34, v35
	v_cvt_pk_bf16_f32 v29, v36, v37
	global_store_dwordx2 v[42:43], v[28:29], off
	v_or_b32_e32 v42, 32, v38
	v_mov_b32_e32 v43, v39
	v_lshl_add_u64 v[42:43], s[62:63], 0, v[42:43]
	v_mul_f32_e32 v35, v35, v35
	v_mul_f32_e32 v37, v37, v37
	v_fmac_f32_e32 v35, v34, v34
	v_fmac_f32_e32 v37, v36, v36
	v_add_f32_e32 v34, v35, v37
	v_mov_b64_e32 v[28:29], v[204:205]
	v_mov_b64_e32 v[30:31], v[206:207]
	v_pk_add_f32 v[30:31], v[26:27], v[30:31]
	v_pk_add_f32 v[28:29], v[24:25], v[28:29]
	s_nop 0
	v_cvt_pk_bf16_f32 v24, v28, v29
	v_cvt_pk_bf16_f32 v25, v30, v31
	global_store_dwordx2 v[42:43], v[24:25], off
	v_or_b32_e32 v42, 0x100, v38
	v_mov_b32_e32 v43, v39
	v_lshl_add_u64 v[42:43], s[62:63], 0, v[42:43]
	v_mul_f32_e32 v29, v29, v29
	v_mul_f32_e32 v31, v31, v31
	v_fmac_f32_e32 v29, v28, v28
	v_fmac_f32_e32 v31, v30, v30
	v_add_f32_e32 v28, v29, v31
	v_add_f32_e32 v28, v34, v28
	v_or_b32_e32 v38, 0x120, v38
	v_mov_b64_e32 v[24:25], v[208:209]
	v_mov_b64_e32 v[26:27], v[210:211]
	v_pk_add_f32 v[26:27], v[22:23], v[26:27]
	v_pk_add_f32 v[24:25], v[20:21], v[24:25]
	s_nop 0
	v_cvt_pk_bf16_f32 v20, v24, v25
	v_cvt_pk_bf16_f32 v21, v26, v27
	global_store_dwordx2 v[42:43], v[20:21], off
	v_mul_f32_e32 v25, v25, v25
	v_mul_f32_e32 v27, v27, v27
	v_fmac_f32_e32 v25, v24, v24
	v_fmac_f32_e32 v27, v26, v26
	v_add_f32_e32 v24, v25, v27
	v_add_f32_e32 v24, v28, v24
	v_mov_b64_e32 v[20:21], v[212:213]
	v_mov_b64_e32 v[22:23], v[214:215]
	v_pk_add_f32 v[18:19], v[18:19], v[22:23]
	v_pk_add_f32 v[16:17], v[16:17], v[20:21]
	v_mul_f32_e32 v21, v19, v19
	v_mul_f32_e32 v20, v17, v17
	v_fmac_f32_e32 v20, v16, v16
	v_fmac_f32_e32 v21, v18, v18
	v_add_f32_e32 v20, v20, v21
	v_add_f32_e32 v21, v24, v20
	ds_bpermute_b32 v22, v116, v21
	v_cvt_pk_bf16_f32 v20, v16, v17
	s_waitcnt lgkmcnt(0)
	v_add_f32_e32 v16, v21, v22
	ds_bpermute_b32 v17, v114, v16
	v_cvt_pk_bf16_f32 v21, v18, v19
	v_lshl_add_u64 v[18:19], s[62:63], 0, v[38:39]
	global_store_dwordx2 v[18:19], v[20:21], off
	s_and_saveexec_b64 s[30:31], s[4:5]
	s_cbranch_execz .LBB0_725
	v_lshlrev_b64 v[18:19], 6, v[32:33]
	v_lshl_add_u64 v[18:19], s[60:61], 0, v[18:19]
	v_lshl_add_u64 v[18:19], s[28:29], 2, v[18:19]
	s_lshl_b32 s8, s47, 2
	v_lshl_add_u64 v[18:19], v[18:19], 0, s[8:9]
	s_waitcnt lgkmcnt(0)
	v_add_f32_e32 v16, v16, v17
	global_store_dword v[18:19], v16, off
.LBB0_725:
	s_or_b64 exec, exec, s[30:31]
	v_add_u32_e32 v16, 0xb0, v144
	s_waitcnt lgkmcnt(0)
	v_ashrrev_i32_e32 v17, 31, v16
	v_lshlrev_b64 v[18:19], 10, v[16:17]
	v_lshl_add_u64 v[22:23], v[18:19], 0, v[142:143]
	v_lshl_add_u64 v[24:25], v[22:23], 2, s[52:53]
	v_lshlrev_b64 v[22:23], 1, v[22:23]
	v_lshl_add_u64 v[26:27], s[62:63], 0, v[22:23]
	v_mov_b64_e32 v[18:19], v[216:217]
	v_mov_b64_e32 v[20:21], v[218:219]
	v_pk_add_f32 v[20:21], v[14:15], v[20:21]
	v_pk_add_f32 v[18:19], v[12:13], v[18:19]
	s_nop 0
	v_cvt_pk_bf16_f32 v12, v18, v19
	v_cvt_pk_bf16_f32 v13, v20, v21
	global_store_dwordx2 v[26:27], v[12:13], off
	v_or_b32_e32 v26, 32, v22
	v_mov_b32_e32 v27, v23
	v_lshl_add_u64 v[26:27], s[62:63], 0, v[26:27]
	v_mul_f32_e32 v19, v19, v19
	v_mul_f32_e32 v21, v21, v21
	v_fmac_f32_e32 v19, v18, v18
	v_fmac_f32_e32 v21, v20, v20
	v_add_f32_e32 v18, v19, v21
	v_mov_b64_e32 v[12:13], v[220:221]
	v_mov_b64_e32 v[14:15], v[222:223]
	v_pk_add_f32 v[14:15], v[10:11], v[14:15]
	v_pk_add_f32 v[12:13], v[8:9], v[12:13]
	s_nop 0
	v_cvt_pk_bf16_f32 v8, v12, v13
	v_cvt_pk_bf16_f32 v9, v14, v15
	global_store_dwordx2 v[26:27], v[8:9], off
	v_or_b32_e32 v26, 0x100, v22
	v_mov_b32_e32 v27, v23
	v_lshl_add_u64 v[26:27], s[62:63], 0, v[26:27]
	v_mul_f32_e32 v13, v13, v13
	v_mul_f32_e32 v15, v15, v15
	v_fmac_f32_e32 v13, v12, v12
	v_fmac_f32_e32 v15, v14, v14
	v_add_f32_e32 v12, v13, v15
	v_add_f32_e32 v12, v18, v12
	v_or_b32_e32 v22, 0x120, v22
	v_mov_b64_e32 v[8:9], v[224:225]
	v_mov_b64_e32 v[10:11], v[226:227]
	v_pk_add_f32 v[10:11], v[6:7], v[10:11]
	v_pk_add_f32 v[8:9], v[4:5], v[8:9]
	s_nop 0
	v_cvt_pk_bf16_f32 v4, v8, v9
	v_cvt_pk_bf16_f32 v5, v10, v11
	global_store_dwordx2 v[26:27], v[4:5], off
	v_mul_f32_e32 v9, v9, v9
	v_mul_f32_e32 v11, v11, v11
	v_fmac_f32_e32 v9, v8, v8
	v_fmac_f32_e32 v11, v10, v10
	v_add_f32_e32 v8, v9, v11
	v_add_f32_e32 v8, v12, v8
	v_mov_b64_e32 v[4:5], v[228:229]
	v_mov_b64_e32 v[6:7], v[230:231]
	v_pk_add_f32 v[2:3], v[2:3], v[6:7]
	v_pk_add_f32 v[0:1], v[0:1], v[4:5]
	v_mul_f32_e32 v5, v3, v3
	v_mul_f32_e32 v4, v1, v1
	v_fmac_f32_e32 v4, v0, v0
	v_fmac_f32_e32 v5, v2, v2
	v_add_f32_e32 v4, v4, v5
	v_add_f32_e32 v5, v8, v4
	ds_bpermute_b32 v6, v116, v5
	v_cvt_pk_bf16_f32 v4, v0, v1
	s_waitcnt lgkmcnt(0)
	v_add_f32_e32 v0, v5, v6
	ds_bpermute_b32 v1, v114, v0
	v_cvt_pk_bf16_f32 v5, v2, v3
	v_lshl_add_u64 v[2:3], s[62:63], 0, v[22:23]
	global_store_dwordx2 v[2:3], v[4:5], off
	s_and_saveexec_b64 s[30:31], s[4:5]
	s_cbranch_execz .LBB0_727
	v_lshlrev_b64 v[2:3], 6, v[16:17]
	v_lshl_add_u64 v[2:3], s[60:61], 0, v[2:3]
	v_lshl_add_u64 v[2:3], s[28:29], 2, v[2:3]
	s_lshl_b32 s8, s47, 2
	v_lshl_add_u64 v[2:3], v[2:3], 0, s[8:9]
	s_waitcnt lgkmcnt(0)
	v_add_f32_e32 v0, v0, v1
	global_store_dword v[2:3], v0, off
